# phase-0 x->out copy removed: layer-0 first norm reads x, layer-0 first residual GEMM loads x and stores to out
# speedup vs baseline: 1.0091x; 1.0072x over previous
; #define GETLANE() int lane; asm volatile("v_mbcnt_lo_u32_b32 %0, -1, 0\n\tv_mbcnt_hi_u32_b32 %0, -1, %0" : "=v"(lane)); const int tid = wave * 64 + lane
;     __device__ __forceinline__ bool next(int i, pg8::Unit& u) const {
;         const int L = i * G + c;
;         if (L < n_lat) {
;             const int wgid = (L & 7) * (n_lat >> 3) + (L >> 3), nig = 8 * nN, w = wgid % nig;
;             u.pm = (((wgid / nig) ^ (ksplit >> 8)) * 8 + (w & 7)) | (ntfull << 16); u.pn = w >> 3; return true; }
;         const int q = L - n_lat; if (q >= n_ctx) return false;
;         const int ksp = ksplit & 0xff, ks = q % ksp, rest = q / ksp; u.pn = (rest % nN) | (ks << 16) | (ksp > 1 ? (1 << 30) : 0); u.pm = (128 + rest / nN) | ((ntfull / ksp) << 16); return true;
; __global__ void __launch_bounds__(NTHR) fwd_megakernel(Args a_unused) {
;     ...
;             else if (j == 2 || j == 9 || j == 12) {
;                 GETLANE(); (void)lane;
;                 const bf16_t* A = j == 9 ? XN : (const bf16_t*)(ws + OFF_HFF);
;                 const bf16_t* Bt = (const bf16_t*)(wb + (j == 2 ? W_FFN1_OUT : (j == 9 ? W_OUT : W_FFN2_OUT)));
;                 const int Kd = j == 9 ? D : DFF;
;                 pg8::Gemm g{A, Bt, MTOT, D, Kd}; CtxOrder S; S.init(D, Kd, G, bid, nctx, j == 9 ? 4 : 11, j == 9 ? 0 : 1);
;                 EpiResid E{hl, hc, modl + (j == 2 ? 2 : (j == 9 ? 5 : 8)) * 1024, j == 9 ? 1.0f : 0.5f}; pg8::gemm_phase<EpiResid, CtxOrder, true, true>(lds, g, S, E, tid); }
.LBB0_37:
	s_mov_b32 s14, s62
	v_writelane_b32 v254, s14, 52
	s_and_b64 vcc, exec, s[20:21]
	s_nop 0
	v_writelane_b32 v254, s15, 53
	s_cbranch_vccz .LBB0_75
	s_mov_b64 s[96:97], 0
	s_cmp_lg_u32 s62, 0
	s_cbranch_scc1 .Ldelta_done
	s_cmp_lg_u32 s87, 2
	s_cbranch_scc1 .Ldelta_done
	s_load_dwordx2 s[96:97], s[30:31], 0x0
	s_waitcnt lgkmcnt(0)
	s_sub_u32 s96, s96, s8
	s_subb_u32 s97, s97, s9
.Ldelta_done:
	s_cmp_eq_u32 s87, 9
	s_cselect_b64 s[20:21], -1, 0
	v_readlane_b32 s12, v254, 48
	v_mbcnt_lo_u32_b32 v14, -1, 0
	v_mbcnt_hi_u32_b32 v14, -1, v14
	s_nop 1
	v_lshl_add_u32 v1, s12, 6, v14
	s_and_b64 s[12:13], s[20:21], exec
	s_movk_i32 s12, 0x400
	s_cselect_b32 s47, 4, 11
	s_cselect_b32 s16, s12, 0xb00
	s_mul_i32 s12, s46, s47
	s_cselect_b32 s28, 4, 0x10b
	s_lshl_b32 s48, s12, 2
	v_readfirstlane_b32 s29, v1
	s_cmpk_gt_i32 s89, 0x1ff
	s_mov_b64 s[12:13], -1
	s_cbranch_scc0 .LBB0_41
	s_add_i32 s14, s89, 0xfffffe00
	s_mov_b64 s[12:13], 0
	s_cmp_ge_u32 s14, s48
	s_mov_b64 s[14:15], 0
	s_cbranch_scc1 .LBB0_41
	v_cvt_f32_ubyte0_e32 v3, s47
	v_rcp_iflag_f32_e32 v4, v3
	v_cvt_f32_ubyte0_e32 v2, s89
	s_lshr_b32 s26, s16, 6
	v_mul_f32_e32 v5, v2, v4
	v_trunc_f32_e32 v5, v5
	v_fma_f32 v2, -v5, v3, v2
	v_cvt_u32_f32_e32 v5, v5
	v_cmp_ge_f32_e64 s[14:15], |v2|, v3
	s_cmp_lg_u64 s[14:15], 0
	v_cvt_f32_ubyte0_e32 v2, s26
	v_readfirstlane_b32 s27, v5
	s_addc_u32 s14, s27, 0
	s_mul_i32 s15, s14, s47
	v_mul_f32_e32 v4, v2, v4
	s_sub_i32 s15, s89, s15
	v_trunc_f32_e32 v4, v4
	s_and_b32 s15, s15, 0xff
	v_fma_f32 v2, -v4, v3, v2
	v_cvt_u32_f32_e32 v4, v4
	s_and_b32 s27, s14, 3
	s_lshl_b32 s15, s15, 16
	s_lshr_b32 s14, s14, 2
	s_or_b32 s15, s15, s27
	s_bitset1_b32 s14, 7
	s_or_b32 s73, s15, 2.0
	s_and_b32 s27, s14, 0xbf
	v_cmp_ge_f32_e64 s[14:15], |v2|, v3
	v_readfirstlane_b32 s26, v4
	s_cmp_lg_u64 s[14:15], 0
	s_addc_u32 s14, s26, 0
	s_and_b32 s14, s14, 63
	s_lshl_b32 s14, s14, 16
	s_or_b32 s76, s14, s27
	s_mov_b64 s[14:15], -1

;     __device__ __forceinline__ void operator()(const pg8::f32x4 (&acc)[2][2][4][2], const pg8::Unit& uu, int wr, int wc, int fr, int fq) const {
;     ...
;         if (!((uu.pn >> 30) & 1)) {
; #pragma unroll
;             for (int ai = 0; ai < 2; ++ai)
; #pragma unroll
;                 for (int m = 0; m < 4; ++m) { float* rowp = base + (size_t)(wr * 64 + fr + ai * 128 + m * 16) * D + col0;
; #pragma unroll
;                     for (int bj = 0; bj < 2; ++bj)
; #pragma unroll
;                         for (int n = 0; n < 2; ++n) { pg8::f32x4* p = (pg8::f32x4*)(rowp + bj * 128 + 4 * n); *p = *p + gv[bj][n] * acc[ai][bj][m][n]; } }
.LBB0_72:
	v_add_u32_e32 v164, s63, v169
	v_ashrrev_i32_e32 v165, 31, v164
	v_lshl_add_u64 v[162:163], v[162:163], 2, s[40:41]
	v_lshlrev_b64 v[164:165], 12, v[164:165]
	v_lshl_add_u64 v[162:163], v[162:163], 0, v[164:165]
	s_mov_b32 s41, 0
	v_lshl_add_u64 v[250:251], v[162:163], 0, s[96:97]
	global_load_dwordx4 v[170:173], v[250:251], off
	global_load_dwordx4 v[174:177], v[250:251], off offset:16
	global_load_dwordx4 v[178:181], v[250:251], off offset:512
	global_load_dwordx4 v[182:185], v[250:251], off offset:528
	s_mov_b32 s40, 0x10000
	v_lshl_add_u64 v[164:165], v[162:163], 0, s[40:41]
	v_lshl_add_u64 v[250:251], v[164:165], 0, s[96:97]
	global_load_dwordx4 v[186:189], v[250:251], off
	global_load_dwordx4 v[192:195], v[250:251], off offset:16
	global_load_dwordx4 v[196:199], v[250:251], off offset:512
	global_load_dwordx4 v[200:203], v[250:251], off offset:528
	s_mov_b32 s40, 0x20000
	v_lshl_add_u64 v[238:239], v[162:163], 0, s[40:41]
	v_lshl_add_u64 v[250:251], v[238:239], 0, s[96:97]
	global_load_dwordx4 v[218:221], v[250:251], off
	global_load_dwordx4 v[222:225], v[250:251], off offset:16
	global_load_dwordx4 v[230:233], v[250:251], off offset:512
	global_load_dwordx4 v[234:237], v[250:251], off offset:528
	s_mov_b32 s40, 0x30000
	v_lshl_add_u64 v[240:241], v[162:163], 0, s[40:41]
	s_mov_b32 s40, 0x80000
	v_lshl_add_u64 v[242:243], v[162:163], 0, s[40:41]
	s_mov_b32 s40, 0x90000
	v_lshl_add_u64 v[244:245], v[162:163], 0, s[40:41]
	s_mov_b32 s40, 0xa0000
	v_lshl_add_u64 v[246:247], v[162:163], 0, s[40:41]
	s_mov_b32 s40, 0xb0000
	v_lshl_add_u64 v[248:249], v[162:163], 0, s[40:41]
	s_mov_b32 s16, 0xb0000
	s_waitcnt vmcnt(8)
	v_pk_fma_f32 v[126:127], v[126:127], v[160:161], v[170:171]
	v_pk_fma_f32 v[128:129], v[128:129], v[158:159], v[172:173]
	v_pk_fma_f32 v[122:123], v[122:123], v[156:157], v[174:175]
	v_pk_fma_f32 v[124:125], v[124:125], v[154:155], v[176:177]
	v_pk_fma_f32 v[118:119], v[118:119], v[152:153], v[178:179]
	v_pk_fma_f32 v[120:121], v[120:121], v[150:151], v[180:181]
	v_pk_fma_f32 v[114:115], v[114:115], v[148:149], v[182:183]
	v_pk_fma_f32 v[116:117], v[116:117], v[146:147], v[184:185]
	global_store_dwordx4 v[162:163], v[126:129], off
	global_store_dwordx4 v[162:163], v[122:125], off offset:16
	global_store_dwordx4 v[162:163], v[118:121], off offset:512
	global_store_dwordx4 v[162:163], v[114:117], off offset:528
	v_lshl_add_u64 v[250:251], v[240:241], 0, s[96:97]
	global_load_dwordx4 v[170:173], v[250:251], off
	global_load_dwordx4 v[174:177], v[250:251], off offset:16
	global_load_dwordx4 v[178:181], v[250:251], off offset:512
	global_load_dwordx4 v[182:185], v[250:251], off offset:528
	s_waitcnt vmcnt(12)
	v_pk_fma_f32 v[110:111], v[110:111], v[160:161], v[186:187]
	v_pk_fma_f32 v[112:113], v[112:113], v[158:159], v[188:189]
	v_pk_fma_f32 v[106:107], v[106:107], v[156:157], v[192:193]
	v_pk_fma_f32 v[108:109], v[108:109], v[154:155], v[194:195]
	v_pk_fma_f32 v[102:103], v[102:103], v[152:153], v[196:197]
	v_pk_fma_f32 v[104:105], v[104:105], v[150:151], v[198:199]
	v_pk_fma_f32 v[98:99], v[98:99], v[148:149], v[200:201]
	v_pk_fma_f32 v[100:101], v[100:101], v[146:147], v[202:203]
	global_store_dwordx4 v[164:165], v[110:113], off
	global_store_dwordx4 v[164:165], v[106:109], off offset:16
	global_store_dwordx4 v[164:165], v[102:105], off offset:512
	global_store_dwordx4 v[164:165], v[98:101], off offset:528
	v_lshl_add_u64 v[250:251], v[242:243], 0, s[96:97]
	global_load_dwordx4 v[186:189], v[250:251], off
	global_load_dwordx4 v[192:195], v[250:251], off offset:16
	global_load_dwordx4 v[196:199], v[250:251], off offset:512
	global_load_dwordx4 v[200:203], v[250:251], off offset:528
	s_waitcnt vmcnt(16)
	v_pk_fma_f32 v[94:95], v[94:95], v[160:161], v[218:219]
	v_pk_fma_f32 v[96:97], v[96:97], v[158:159], v[220:221]
	v_pk_fma_f32 v[90:91], v[90:91], v[156:157], v[222:223]
	v_pk_fma_f32 v[92:93], v[92:93], v[154:155], v[224:225]
	v_pk_fma_f32 v[86:87], v[86:87], v[152:153], v[230:231]
	v_pk_fma_f32 v[88:89], v[88:89], v[150:151], v[232:233]
	v_pk_fma_f32 v[82:83], v[82:83], v[148:149], v[234:235]
	v_pk_fma_f32 v[84:85], v[84:85], v[146:147], v[236:237]
	global_store_dwordx4 v[238:239], v[94:97], off
	global_store_dwordx4 v[238:239], v[90:93], off offset:16
	global_store_dwordx4 v[238:239], v[86:89], off offset:512
	global_store_dwordx4 v[238:239], v[82:85], off offset:528
	v_lshl_add_u64 v[250:251], v[244:245], 0, s[96:97]
	global_load_dwordx4 v[218:221], v[250:251], off
	global_load_dwordx4 v[222:225], v[250:251], off offset:16
	global_load_dwordx4 v[230:233], v[250:251], off offset:512
	global_load_dwordx4 v[234:237], v[250:251], off offset:528
	s_waitcnt vmcnt(16)
;     __device__ __forceinline__ void operator()(const pg8::f32x4 (&acc)[2][2][4][2], const pg8::Unit& uu, int wr, int wc, int fr, int fq) const {
;     ...
;         if (!((uu.pn >> 30) & 1)) {
; #pragma unroll
;             for (int ai = 0; ai < 2; ++ai)
; #pragma unroll
;                 for (int m = 0; m < 4; ++m) { float* rowp = base + (size_t)(wr * 64 + fr + ai * 128 + m * 16) * D + col0;
; #pragma unroll
;                     for (int bj = 0; bj < 2; ++bj)
; #pragma unroll
;                         for (int n = 0; n < 2; ++n) { pg8::f32x4* p = (pg8::f32x4*)(rowp + bj * 128 + 4 * n); *p = *p + gv[bj][n] * acc[ai][bj][m][n]; } }
	v_pk_fma_f32 v[78:79], v[78:79], v[160:161], v[170:171]
	v_pk_fma_f32 v[80:81], v[80:81], v[158:159], v[172:173]
	v_pk_fma_f32 v[74:75], v[74:75], v[156:157], v[174:175]
	v_pk_fma_f32 v[76:77], v[76:77], v[154:155], v[176:177]
	v_pk_fma_f32 v[70:71], v[70:71], v[152:153], v[178:179]
	v_pk_fma_f32 v[72:73], v[72:73], v[150:151], v[180:181]
	v_pk_fma_f32 v[66:67], v[66:67], v[148:149], v[182:183]
	v_pk_fma_f32 v[68:69], v[68:69], v[146:147], v[184:185]
	global_store_dwordx4 v[240:241], v[78:81], off
	global_store_dwordx4 v[240:241], v[74:77], off offset:16
	global_store_dwordx4 v[240:241], v[70:73], off offset:512
	global_store_dwordx4 v[240:241], v[66:69], off offset:528
	v_lshl_add_u64 v[250:251], v[246:247], 0, s[96:97]
	global_load_dwordx4 v[170:173], v[250:251], off
	global_load_dwordx4 v[174:177], v[250:251], off offset:16
	global_load_dwordx4 v[178:181], v[250:251], off offset:512
	global_load_dwordx4 v[182:185], v[250:251], off offset:528
	s_waitcnt vmcnt(16)
	v_pk_fma_f32 v[62:63], v[62:63], v[160:161], v[186:187]
	v_pk_fma_f32 v[64:65], v[64:65], v[158:159], v[188:189]
	v_pk_fma_f32 v[58:59], v[58:59], v[156:157], v[192:193]
	v_pk_fma_f32 v[60:61], v[60:61], v[154:155], v[194:195]
	v_pk_fma_f32 v[54:55], v[54:55], v[152:153], v[196:197]
	v_pk_fma_f32 v[56:57], v[56:57], v[150:151], v[198:199]
	v_pk_fma_f32 v[50:51], v[50:51], v[148:149], v[200:201]
	v_pk_fma_f32 v[52:53], v[52:53], v[146:147], v[202:203]
	global_store_dwordx4 v[242:243], v[62:65], off
	global_store_dwordx4 v[242:243], v[58:61], off offset:16
	global_store_dwordx4 v[242:243], v[54:57], off offset:512
	global_store_dwordx4 v[242:243], v[50:53], off offset:528
	v_lshl_add_u64 v[250:251], v[248:249], 0, s[96:97]
	global_load_dwordx4 v[186:189], v[250:251], off
	global_load_dwordx4 v[192:195], v[250:251], off offset:16
	global_load_dwordx4 v[196:199], v[250:251], off offset:512
	global_load_dwordx4 v[200:203], v[250:251], off offset:528
	s_waitcnt vmcnt(16)
	v_pk_fma_f32 v[46:47], v[46:47], v[160:161], v[218:219]
	v_pk_fma_f32 v[48:49], v[48:49], v[158:159], v[220:221]
	v_pk_fma_f32 v[42:43], v[42:43], v[156:157], v[222:223]
	v_pk_fma_f32 v[44:45], v[44:45], v[154:155], v[224:225]
	v_pk_fma_f32 v[38:39], v[38:39], v[152:153], v[230:231]
	v_pk_fma_f32 v[40:41], v[40:41], v[150:151], v[232:233]
	v_pk_fma_f32 v[34:35], v[34:35], v[148:149], v[234:235]
	v_pk_fma_f32 v[36:37], v[36:37], v[146:147], v[236:237]
	global_store_dwordx4 v[244:245], v[46:49], off
	global_store_dwordx4 v[244:245], v[42:45], off offset:16
	global_store_dwordx4 v[244:245], v[38:41], off offset:512
	global_store_dwordx4 v[244:245], v[34:37], off offset:528
	s_waitcnt vmcnt(12)
	v_pk_fma_f32 v[30:31], v[30:31], v[160:161], v[170:171]
	v_pk_fma_f32 v[32:33], v[32:33], v[158:159], v[172:173]
	v_pk_fma_f32 v[26:27], v[26:27], v[156:157], v[174:175]
	v_pk_fma_f32 v[28:29], v[28:29], v[154:155], v[176:177]
	v_pk_fma_f32 v[22:23], v[22:23], v[152:153], v[178:179]
	v_pk_fma_f32 v[24:25], v[24:25], v[150:151], v[180:181]
	v_pk_fma_f32 v[18:19], v[18:19], v[148:149], v[182:183]
	v_pk_fma_f32 v[20:21], v[20:21], v[146:147], v[184:185]
	global_store_dwordx4 v[246:247], v[30:33], off
	global_store_dwordx4 v[246:247], v[26:29], off offset:16
	global_store_dwordx4 v[246:247], v[22:25], off offset:512
	global_store_dwordx4 v[246:247], v[18:21], off offset:528
	s_waitcnt vmcnt(8)
	v_pk_fma_f32 v[14:15], v[14:15], v[160:161], v[186:187]
	v_pk_fma_f32 v[16:17], v[16:17], v[158:159], v[188:189]
	v_pk_fma_f32 v[10:11], v[10:11], v[156:157], v[192:193]
	v_pk_fma_f32 v[12:13], v[12:13], v[154:155], v[194:195]
	v_pk_fma_f32 v[6:7], v[6:7], v[152:153], v[196:197]
	v_pk_fma_f32 v[8:9], v[8:9], v[150:151], v[198:199]
	v_pk_fma_f32 v[2:3], v[2:3], v[148:149], v[200:201]
	v_pk_fma_f32 v[4:5], v[4:5], v[146:147], v[202:203]
	global_store_dwordx4 v[248:249], v[14:17], off
	global_store_dwordx4 v[248:249], v[10:13], off offset:16
	global_store_dwordx4 v[248:249], v[6:9], off offset:512
	global_store_dwordx4 v[248:249], v[2:5], off offset:528
	s_and_b64 vcc, exec, s[38:39]
	s_mov_b64 s[38:39], -1
	s_cbranch_vccnz .LBB0_48

; #define GETLANE() int lane; asm volatile("v_mbcnt_lo_u32_b32 %0, -1, 0\n\tv_mbcnt_hi_u32_b32 %0, -1, %0" : "=v"(lane)); const int tid = wave * 64 + lane
; __device__ __forceinline__ void norm_phase(const float* hl, const float* hc, const float* __restrict__ g, const float* __restrict__ modl, int sh_chunk, bf16_t* XN, int gw, int NGW, int lane, int nrows, const float* part, int npieces) {
;     for (int rr = gw; rr < nrows; rr += NGW) {
;         const int row = nrows - 1 - rr;
;         const float* xr = row < MLAT ? hl + (size_t)row * D : hc + (size_t)(row - MLAT) * D;
;         const int mi = row < MLAT ? (row >> 13) : 4;
;         const float* shift = modl + mi * 9216 + sh_chunk * 1024; const float* scale = shift + 1024;
;         f32x4 v[4]; float s = 0.f;
; #pragma unroll
;         for (int j = 0; j < 4; ++j) v[j] = *(const f32x4*)(xr + 4 * lane + 256 * j);
; __global__ void __launch_bounds__(NTHR) fwd_megakernel(Args a_unused) {
;     ...
;             if (j == 0) { GETLANE(); (void)tid; convert_weights(a, l, lds, gw, NGW, wave, lane); norm_phase(hl, hc, a->in[6] + l * D, modl, 0, XN, gw, NGW, lane, MTOT, (const float*)(ws + OFF_PART), l > 0 ? 11 : 0); }
.LBB0_1085:
	s_or_b64 exec, exec, s[2:3]
	s_cmp_gt_i32 s91, 0x83ff
	s_cbranch_scc1 .LBB0_1090
	s_cmp_lg_u32 s62, 0
	s_cbranch_scc1 .Lnorm0_keep
	s_load_dwordx2 s[8:9], s[30:31], 0x0
	s_waitcnt lgkmcnt(0)
.Lnorm0_keep:
	v_readlane_b32 s12, v254, 44
	s_load_dwordx2 s[0:1], s[30:31], 0x30
	v_readlane_b32 s14, v254, 46
	s_cmp_gt_i32 s14, 13
	v_readlane_b32 s13, v254, 45
	s_cselect_b64 s[2:3], -1, 0
	s_lshl_b32 s12, s62, 10
	s_ashr_i32 s13, s12, 31
	s_lshl_b64 s[12:13], s[12:13], 2
	v_lshlrev_b32_e32 v34, 2, v53
	s_waitcnt lgkmcnt(0)
	s_add_u32 s0, s0, s12
	v_ashrrev_i32_e32 v35, 31, v34
	s_addc_u32 s1, s1, s13
	v_lshlrev_b64 v[18:19], 2, v[34:35]
	v_lshl_add_u64 v[14:15], s[0:1], 0, v[18:19]
	global_load_dwordx4 v[2:5], v[14:15], off
	global_load_dwordx4 v[6:9], v[14:15], off offset:1024
	global_load_dwordx4 v[10:13], v[14:15], off offset:2048
	s_nop 0
	global_load_dwordx4 v[14:17], v[14:15], off offset:3072
	v_lshl_add_u64 v[18:19], s[10:11], 0, v[18:19]
	s_mov_b64 s[0:1], 0x207f0000
	v_lshl_add_u64 v[36:37], v[18:19], 0, s[0:1]
	v_readlane_b32 s0, v254, 48
	v_readlane_b32 s1, v254, 49
	s_add_i32 s0, s0, s1
	v_lshl_add_u64 v[38:39], v[34:35], 1, s[74:75]
	s_sub_i32 s0, 0x83ff, s0
	s_xor_b64 s[2:3], s[2:3], -1
	v_readlane_b32 s15, v254, 47
	s_branch .LBB0_1088

; #define LAS __attribute__((address_space(3)))
; __device__ __forceinline__ void p0_phase(ArgP a, LAS unsigned char* lds, int tid, int wave, int lane, int bid, int G) {
;     const int gt = bid * NTHR + tid, GT = G * NTHR;
;     { const f32x4* xs = (const f32x4*)a->in[0]; f32x4* xd = (f32x4*)a->out;
;       for (int i = gt; i < MLAT * D / 4; i += GT) xd[i] = xs[i];
;       const f32x4* cs = (const f32x4*)a->in[2]; f32x4* cd = (f32x4*)(a->ws + OFF_HC);
;       for (int i = gt; i < NB * C * D / 4; i += GT) cd[i] = cs[i]; }
.LBB0_1091:
	s_and_b64 vcc, exec, s[0:1]
	s_cbranch_vccz .LBB0_1127
	v_mbcnt_lo_u32_b32 v2, -1, 0
	v_mbcnt_hi_u32_b32 v2, -1, v2
	s_mov_b32 s1, 0x800000
	v_lshl_add_u32 v4, s16, 6, v2
	v_lshl_add_u32 v6, s89, 9, v4
	s_lshl_b32 s0, s90, 9
.LBB0_1095:
	s_mov_b32 s1, 0x40000
	v_cmp_gt_i32_e32 vcc, s1, v6
	s_and_saveexec_b64 s[2:3], vcc
	s_cbranch_execz .LBB0_1098
	v_ashrrev_i32_e32 v7, 31, v6
	s_ashr_i32 s1, s0, 31
	v_lshlrev_b64 v[8:9], 4, v[6:7]
	s_lshl_b64 s[8:9], s[0:1], 4
	s_mov_b64 s[12:13], 0
